# gated-branch GEMM epilogue: g0 gate loads batched four at a time, z=0 units only
# speedup vs baseline: 1.0104x; 1.0081x over previous
; __device__ __forceinline__ u32x4 pack8(const f32x4 a, const f32x4 b) { u32x4 w; w.x = cvt_pk_bf16(a[0], a[1]); w.y = cvt_pk_bf16(a[2], a[3]); w.z = cvt_pk_bf16(b[0], b[1]); w.w = cvt_pk_bf16(b[2], b[3]); return w; }
; __device__ __forceinline__ float bflo(unsigned w) { return __uint_as_float(w << 16); }
; __device__ __forceinline__ float bfhi(unsigned w) { return __uint_as_float(w & 0xffff0000u); }
;     __device__ __forceinline__ void operator()(f32x4 (&acc)[2][2][4][2], const Unit& u, int wr, int wc, int fr, int fq) const {
;     ...
;             u32x4 g1v[2][2];
; #pragma unroll
;             for (int mm = 0; mm < 2; ++mm)
; #pragma unroll
;                 for (int bj = 0; bj < 2; ++bj) g1v[mm][bj] = *(const u32x4*)(gate + (size_t)(row0 + ai * HALF + (2 * mh + mm) * 16) * 2048 + 1024 + col0 + bj * HALF);
; #pragma unroll
;             for (int mm = 0; mm < 2; ++mm)
; #pragma unroll
;                 for (int bj = 0; bj < 2; ++bj) { const int m = 2 * mh + mm; const int r = row0 + ai * HALF + m * 16; const u32x4 g1 = g1v[mm][bj];
;                     const f32x4 g1a = {bflo(g1.x), bfhi(g1.x), bflo(g1.y), bfhi(g1.y)}, g1b = {bflo(g1.z), bfhi(g1.z), bflo(g1.w), bfhi(g1.w)};
;                     if (u.z == 0) {
;                         const u32x4 g0 = *(const u32x4*)(gate + (size_t)r * 2048 + col0 + bj * HALF);
;                         const f32x4 g0a = {bflo(g0.x), bfhi(g0.x), bflo(g0.y), bfhi(g0.y)}, g0b = {bflo(g0.z), bfhi(g0.z), bflo(g0.w), bfhi(g0.w)};
; #pragma unroll
;                         for (int i = 0; i < 4; ++i) { acc[ai][bj][m][0][i] *= g0a[i] * __builtin_amdgcn_rcpf(__builtin_fmaxf(g1a[i], 1e-30f)); acc[ai][bj][m][1][i] *= g0b[i] * __builtin_amdgcn_rcpf(__builtin_fmaxf(g1b[i], 1e-30f)); }
;                     } else {
;                         *(u32x4*)(merged + (size_t)r * 1024 + col0 + bj * HALF) = pack8(acc[ai][bj][m][0] * g1a, acc[ai][bj][m][1] * g1b); }
.LBB0_770:
	v_lshl_add_u32 v170, s74, 8, v196
	v_lshl_or_b32 v168, s49, 8, v198
	v_ashrrev_i32_e32 v171, 31, v170
	v_ashrrev_i32_e32 v169, 31, v168
	v_lshlrev_b64 v[146:147], 12, v[170:171]
	v_or_b32_e32 v176, 16, v170
	v_lshl_add_u64 v[146:147], s[46:47], 0, v[146:147]
	v_lshlrev_b64 v[172:173], 1, v[168:169]
	v_ashrrev_i32_e32 v177, 31, v176
	v_lshl_add_u64 v[184:185], v[146:147], 0, v[172:173]
	v_lshlrev_b64 v[146:147], 12, v[176:177]
	v_lshl_add_u64 v[146:147], s[46:47], 0, v[146:147]
	v_lshl_add_u64 v[174:175], v[146:147], 0, v[172:173]
	global_load_dwordx4 v[200:203], v[184:185], off offset:2048
	global_load_dwordx4 v[154:157], v[184:185], off offset:2304
	global_load_dwordx4 v[150:153], v[174:175], off offset:2048
	global_load_dwordx4 v[146:149], v[174:175], off offset:2304
	s_cmp_lg_u32 s48, 0
	s_cbranch_scc1 .Lmy_g0_16185
	global_load_dwordx4 v[222:225], v[184:185], off
	global_load_dwordx4 v[226:229], v[184:185], off offset:256
	global_load_dwordx4 v[230:233], v[174:175], off
	global_load_dwordx4 v[234:237], v[174:175], off offset:256
.Lmy_g0_16185:
	s_cmp_lg_u32 s48, 0
	v_lshlrev_b64 v[182:183], 11, v[170:171]
	s_cselect_b64 s[64:65], -1, 0
	v_lshl_add_u64 v[182:183], s[52:53], 0, v[182:183]
	s_and_b64 vcc, exec, s[64:65]
	v_lshl_add_u64 v[186:187], v[168:169], 1, v[182:183]
	s_waitcnt vmcnt(0)
	v_lshlrev_b32_e32 v194, 16, v200
	v_and_b32_e32 v195, 0xffff0000, v200
	v_lshlrev_b32_e32 v190, 16, v201
	v_and_b32_e32 v191, 0xffff0000, v201
	v_lshlrev_b32_e32 v192, 16, v202
	v_and_b32_e32 v193, 0xffff0000, v202
	v_lshlrev_b32_e32 v188, 16, v203
	v_and_b32_e32 v189, 0xffff0000, v203
	s_cbranch_vccz .LBB0_823
	v_pk_mul_f32 v[182:183], v[144:145], v[190:191]
	v_pk_mul_f32 v[200:201], v[142:143], v[194:195]
	v_pk_mul_f32 v[204:205], v[140:141], v[188:189]
	v_pk_mul_f32 v[202:203], v[138:139], v[192:193]
	v_cvt_pk_bf16_f32 v200, v200, v201
	v_cvt_pk_bf16_f32 v201, v182, v183
	v_cvt_pk_bf16_f32 v202, v202, v203
	v_cvt_pk_bf16_f32 v203, v204, v205
	global_store_dwordx4 v[186:187], v[200:203], off
	s_cbranch_execnz .LBB0_773

; __device__ __forceinline__ u32x4 pack8(const f32x4 a, const f32x4 b) { u32x4 w; w.x = cvt_pk_bf16(a[0], a[1]); w.y = cvt_pk_bf16(a[2], a[3]); w.z = cvt_pk_bf16(b[0], b[1]); w.w = cvt_pk_bf16(b[2], b[3]); return w; }
; __device__ __forceinline__ float bflo(unsigned w) { return __uint_as_float(w << 16); }
; __device__ __forceinline__ float bfhi(unsigned w) { return __uint_as_float(w & 0xffff0000u); }
;     __device__ __forceinline__ void operator()(f32x4 (&acc)[2][2][4][2], const Unit& u, int wr, int wc, int fr, int fq) const {
;     ...
;             u32x4 g1v[2][2];
; #pragma unroll
;             for (int mm = 0; mm < 2; ++mm)
; #pragma unroll
;                 for (int bj = 0; bj < 2; ++bj) g1v[mm][bj] = *(const u32x4*)(gate + (size_t)(row0 + ai * HALF + (2 * mh + mm) * 16) * 2048 + 1024 + col0 + bj * HALF);
; #pragma unroll
;             for (int mm = 0; mm < 2; ++mm)
; #pragma unroll
;                 for (int bj = 0; bj < 2; ++bj) { const int m = 2 * mh + mm; const int r = row0 + ai * HALF + m * 16; const u32x4 g1 = g1v[mm][bj];
;                     const f32x4 g1a = {bflo(g1.x), bfhi(g1.x), bflo(g1.y), bfhi(g1.y)}, g1b = {bflo(g1.z), bfhi(g1.z), bflo(g1.w), bfhi(g1.w)};
;                     if (u.z == 0) {
;                         const u32x4 g0 = *(const u32x4*)(gate + (size_t)r * 2048 + col0 + bj * HALF);
;                         const f32x4 g0a = {bflo(g0.x), bfhi(g0.x), bflo(g0.y), bfhi(g0.y)}, g0b = {bflo(g0.z), bfhi(g0.z), bflo(g0.w), bfhi(g0.w)};
; #pragma unroll
;                         for (int i = 0; i < 4; ++i) { acc[ai][bj][m][0][i] *= g0a[i] * __builtin_amdgcn_rcpf(__builtin_fmaxf(g1a[i], 1e-30f)); acc[ai][bj][m][1][i] *= g0b[i] * __builtin_amdgcn_rcpf(__builtin_fmaxf(g1b[i], 1e-30f)); }
;                     } else {
;                         *(u32x4*)(merged + (size_t)r * 1024 + col0 + bj * HALF) = pack8(acc[ai][bj][m][0] * g1a, acc[ai][bj][m][1] * g1b); }
.LBB0_782:
	v_or_b32_e32 v182, 32, v170
	v_ashrrev_i32_e32 v183, 31, v182
	v_lshlrev_b64 v[146:147], 12, v[182:183]
	v_or_b32_e32 v176, 48, v170
	v_lshl_add_u64 v[146:147], s[46:47], 0, v[146:147]
	v_ashrrev_i32_e32 v177, 31, v176
	v_lshl_add_u64 v[184:185], v[146:147], 0, v[172:173]
	v_lshlrev_b64 v[146:147], 12, v[176:177]
	v_lshl_add_u64 v[146:147], s[46:47], 0, v[146:147]
	global_load_dwordx4 v[186:189], v[184:185], off offset:2048
	v_lshl_add_u64 v[174:175], v[146:147], 0, v[172:173]
	global_load_dwordx4 v[154:157], v[184:185], off offset:2304
	global_load_dwordx4 v[150:153], v[174:175], off offset:2048
	global_load_dwordx4 v[146:149], v[174:175], off offset:2304
	s_cmp_lg_u32 s48, 0
	s_cbranch_scc1 .Lmy_g0_16481
	global_load_dwordx4 v[222:225], v[184:185], off
	global_load_dwordx4 v[226:229], v[184:185], off offset:256
	global_load_dwordx4 v[230:233], v[174:175], off
	global_load_dwordx4 v[234:237], v[174:175], off offset:256
.Lmy_g0_16481:
	v_lshlrev_b64 v[182:183], 11, v[182:183]
	v_lshl_add_u64 v[182:183], s[52:53], 0, v[182:183]
	s_and_b64 vcc, exec, s[42:43]
	s_waitcnt vmcnt(3)
	v_lshlrev_b32_e32 v194, 16, v186
	v_and_b32_e32 v195, 0xffff0000, v186
	v_lshlrev_b32_e32 v190, 16, v187
	v_and_b32_e32 v191, 0xffff0000, v187
	v_lshlrev_b32_e32 v192, 16, v188
	v_and_b32_e32 v193, 0xffff0000, v188
	v_lshlrev_b32_e32 v188, 16, v189
	v_and_b32_e32 v189, 0xffff0000, v189
	v_lshl_add_u64 v[186:187], v[168:169], 1, v[182:183]
	s_cbranch_vccnz .LBB0_827
	v_pk_mul_f32 v[182:183], v[128:129], v[190:191]
	v_pk_mul_f32 v[200:201], v[126:127], v[194:195]
	v_pk_mul_f32 v[204:205], v[124:125], v[188:189]
	v_pk_mul_f32 v[202:203], v[122:123], v[192:193]
	v_cvt_pk_bf16_f32 v200, v200, v201
	v_cvt_pk_bf16_f32 v201, v182, v183
	v_cvt_pk_bf16_f32 v202, v202, v203
	v_cvt_pk_bf16_f32 v203, v204, v205
	global_store_dwordx4 v[186:187], v[200:203], off
	s_cbranch_execnz .LBB0_785

; __device__ __forceinline__ u32x4 pack8(const f32x4 a, const f32x4 b) { u32x4 w; w.x = cvt_pk_bf16(a[0], a[1]); w.y = cvt_pk_bf16(a[2], a[3]); w.z = cvt_pk_bf16(b[0], b[1]); w.w = cvt_pk_bf16(b[2], b[3]); return w; }
; __device__ __forceinline__ float bflo(unsigned w) { return __uint_as_float(w << 16); }
; __device__ __forceinline__ float bfhi(unsigned w) { return __uint_as_float(w & 0xffff0000u); }
;     __device__ __forceinline__ void operator()(f32x4 (&acc)[2][2][4][2], const Unit& u, int wr, int wc, int fr, int fq) const {
;     ...
;             u32x4 g1v[2][2];
; #pragma unroll
;             for (int mm = 0; mm < 2; ++mm)
; #pragma unroll
;                 for (int bj = 0; bj < 2; ++bj) g1v[mm][bj] = *(const u32x4*)(gate + (size_t)(row0 + ai * HALF + (2 * mh + mm) * 16) * 2048 + 1024 + col0 + bj * HALF);
; #pragma unroll
;             for (int mm = 0; mm < 2; ++mm)
; #pragma unroll
;                 for (int bj = 0; bj < 2; ++bj) { const int m = 2 * mh + mm; const int r = row0 + ai * HALF + m * 16; const u32x4 g1 = g1v[mm][bj];
;                     const f32x4 g1a = {bflo(g1.x), bfhi(g1.x), bflo(g1.y), bfhi(g1.y)}, g1b = {bflo(g1.z), bfhi(g1.z), bflo(g1.w), bfhi(g1.w)};
;                     if (u.z == 0) {
;                         const u32x4 g0 = *(const u32x4*)(gate + (size_t)r * 2048 + col0 + bj * HALF);
;                         const f32x4 g0a = {bflo(g0.x), bfhi(g0.x), bflo(g0.y), bfhi(g0.y)}, g0b = {bflo(g0.z), bfhi(g0.z), bflo(g0.w), bfhi(g0.w)};
; #pragma unroll
;                         for (int i = 0; i < 4; ++i) { acc[ai][bj][m][0][i] *= g0a[i] * __builtin_amdgcn_rcpf(__builtin_fmaxf(g1a[i], 1e-30f)); acc[ai][bj][m][1][i] *= g0b[i] * __builtin_amdgcn_rcpf(__builtin_fmaxf(g1b[i], 1e-30f)); }
;                     } else {
;                         *(u32x4*)(merged + (size_t)r * 1024 + col0 + bj * HALF) = pack8(acc[ai][bj][m][0] * g1a, acc[ai][bj][m][1] * g1b); }
.LBB0_794:
	v_add_u32_e32 v182, 0x80, v170
	v_ashrrev_i32_e32 v183, 31, v182
	v_lshlrev_b64 v[146:147], 12, v[182:183]
	v_add_u32_e32 v176, 0x90, v170
	v_lshl_add_u64 v[146:147], s[46:47], 0, v[146:147]
	v_ashrrev_i32_e32 v177, 31, v176
	v_lshl_add_u64 v[184:185], v[146:147], 0, v[172:173]
	v_lshlrev_b64 v[146:147], 12, v[176:177]
	v_lshl_add_u64 v[146:147], s[46:47], 0, v[146:147]
	global_load_dwordx4 v[186:189], v[184:185], off offset:2048
	v_lshl_add_u64 v[174:175], v[146:147], 0, v[172:173]
	global_load_dwordx4 v[154:157], v[184:185], off offset:2304
	global_load_dwordx4 v[150:153], v[174:175], off offset:2048
	global_load_dwordx4 v[146:149], v[174:175], off offset:2304
	s_cmp_lg_u32 s48, 0
	s_cbranch_scc1 .Lmy_g0_16776
	global_load_dwordx4 v[222:225], v[184:185], off
	global_load_dwordx4 v[226:229], v[184:185], off offset:256
	global_load_dwordx4 v[230:233], v[174:175], off
	global_load_dwordx4 v[234:237], v[174:175], off offset:256
.Lmy_g0_16776:
	v_lshlrev_b64 v[182:183], 11, v[182:183]
	v_lshl_add_u64 v[182:183], s[52:53], 0, v[182:183]
	s_and_b64 vcc, exec, s[42:43]
	s_waitcnt vmcnt(3)
	v_lshlrev_b32_e32 v194, 16, v186
	v_and_b32_e32 v195, 0xffff0000, v186
	v_lshlrev_b32_e32 v190, 16, v187
	v_and_b32_e32 v191, 0xffff0000, v187
	v_lshlrev_b32_e32 v192, 16, v188
	v_and_b32_e32 v193, 0xffff0000, v188
	v_lshlrev_b32_e32 v188, 16, v189
	v_and_b32_e32 v189, 0xffff0000, v189
	v_lshl_add_u64 v[186:187], v[168:169], 1, v[182:183]
	s_cbranch_vccnz .LBB0_831
	v_pk_mul_f32 v[182:183], v[80:81], v[190:191]
	v_pk_mul_f32 v[200:201], v[78:79], v[194:195]
	v_pk_mul_f32 v[204:205], v[76:77], v[188:189]
	v_pk_mul_f32 v[202:203], v[74:75], v[192:193]
	v_cvt_pk_bf16_f32 v200, v200, v201
	v_cvt_pk_bf16_f32 v201, v182, v183
	v_cvt_pk_bf16_f32 v202, v202, v203
	v_cvt_pk_bf16_f32 v203, v204, v205
	global_store_dwordx4 v[186:187], v[200:203], off
	s_cbranch_execnz .LBB0_797

; __device__ __forceinline__ u32x4 pack8(const f32x4 a, const f32x4 b) { u32x4 w; w.x = cvt_pk_bf16(a[0], a[1]); w.y = cvt_pk_bf16(a[2], a[3]); w.z = cvt_pk_bf16(b[0], b[1]); w.w = cvt_pk_bf16(b[2], b[3]); return w; }
; __device__ __forceinline__ float bflo(unsigned w) { return __uint_as_float(w << 16); }
; __device__ __forceinline__ float bfhi(unsigned w) { return __uint_as_float(w & 0xffff0000u); }
;     __device__ __forceinline__ void operator()(f32x4 (&acc)[2][2][4][2], const Unit& u, int wr, int wc, int fr, int fq) const {
;     ...
;             u32x4 g1v[2][2];
; #pragma unroll
;             for (int mm = 0; mm < 2; ++mm)
; #pragma unroll
;                 for (int bj = 0; bj < 2; ++bj) g1v[mm][bj] = *(const u32x4*)(gate + (size_t)(row0 + ai * HALF + (2 * mh + mm) * 16) * 2048 + 1024 + col0 + bj * HALF);
; #pragma unroll
;             for (int mm = 0; mm < 2; ++mm)
; #pragma unroll
;                 for (int bj = 0; bj < 2; ++bj) { const int m = 2 * mh + mm; const int r = row0 + ai * HALF + m * 16; const u32x4 g1 = g1v[mm][bj];
;                     const f32x4 g1a = {bflo(g1.x), bfhi(g1.x), bflo(g1.y), bfhi(g1.y)}, g1b = {bflo(g1.z), bfhi(g1.z), bflo(g1.w), bfhi(g1.w)};
;                     if (u.z == 0) {
;                         const u32x4 g0 = *(const u32x4*)(gate + (size_t)r * 2048 + col0 + bj * HALF);
;                         const f32x4 g0a = {bflo(g0.x), bfhi(g0.x), bflo(g0.y), bfhi(g0.y)}, g0b = {bflo(g0.z), bfhi(g0.z), bflo(g0.w), bfhi(g0.w)};
; #pragma unroll
;                         for (int i = 0; i < 4; ++i) { acc[ai][bj][m][0][i] *= g0a[i] * __builtin_amdgcn_rcpf(__builtin_fmaxf(g1a[i], 1e-30f)); acc[ai][bj][m][1][i] *= g0b[i] * __builtin_amdgcn_rcpf(__builtin_fmaxf(g1b[i], 1e-30f)); }
;                     } else {
;                         *(u32x4*)(merged + (size_t)r * 1024 + col0 + bj * HALF) = pack8(acc[ai][bj][m][0] * g1a, acc[ai][bj][m][1] * g1b); }
.LBB0_806:
	v_add_u32_e32 v182, 0xa0, v170
	v_ashrrev_i32_e32 v183, 31, v182
	v_lshlrev_b64 v[146:147], 12, v[182:183]
	v_add_u32_e32 v174, 0xb0, v170
	v_lshl_add_u64 v[146:147], s[46:47], 0, v[146:147]
	v_ashrrev_i32_e32 v175, 31, v174
	v_lshl_add_u64 v[176:177], v[146:147], 0, v[172:173]
	v_lshlrev_b64 v[146:147], 12, v[174:175]
	v_lshl_add_u64 v[146:147], s[46:47], 0, v[146:147]
	global_load_dwordx4 v[192:195], v[176:177], off offset:2048
	v_lshl_add_u64 v[170:171], v[146:147], 0, v[172:173]
	global_load_dwordx4 v[154:157], v[176:177], off offset:2304
	global_load_dwordx4 v[150:153], v[170:171], off offset:2048
	global_load_dwordx4 v[146:149], v[170:171], off offset:2304
	s_cmp_lg_u32 s48, 0
	s_cbranch_scc1 .Lmy_g0_17071
	global_load_dwordx4 v[222:225], v[176:177], off
	global_load_dwordx4 v[226:229], v[176:177], off offset:256
	global_load_dwordx4 v[230:233], v[170:171], off
	global_load_dwordx4 v[234:237], v[170:171], off offset:256
.Lmy_g0_17071:
	v_lshlrev_b64 v[172:173], 11, v[182:183]
	v_lshl_add_u64 v[172:173], s[52:53], 0, v[172:173]
	s_and_b64 vcc, exec, s[42:43]
	v_lshl_add_u64 v[172:173], v[168:169], 1, v[172:173]
	s_waitcnt vmcnt(3)
	v_lshlrev_b32_e32 v190, 16, v192
	v_and_b32_e32 v191, 0xffff0000, v192
	v_lshlrev_b32_e32 v186, 16, v193
	v_and_b32_e32 v187, 0xffff0000, v193
	v_lshlrev_b32_e32 v188, 16, v194
	v_and_b32_e32 v189, 0xffff0000, v194
	v_lshlrev_b32_e32 v184, 16, v195
	v_and_b32_e32 v185, 0xffff0000, v195
	s_cbranch_vccnz .LBB0_835
	v_pk_mul_f32 v[182:183], v[64:65], v[186:187]
	v_pk_mul_f32 v[192:193], v[62:63], v[190:191]
	v_pk_mul_f32 v[200:201], v[60:61], v[184:185]
	v_pk_mul_f32 v[194:195], v[58:59], v[188:189]
	v_cvt_pk_bf16_f32 v192, v192, v193
	v_cvt_pk_bf16_f32 v193, v182, v183
	v_cvt_pk_bf16_f32 v194, v194, v195
	v_cvt_pk_bf16_f32 v195, v200, v201
	global_store_dwordx4 v[172:173], v[192:195], off
	s_cbranch_execnz .LBB0_809
